# static s_setprio 1 for waves 4-7 at entry of the attention/HGRN unit phases (P2, P4), on top of the GEMM-loop setprio/barrier edits
# baseline (speedup 1.0000x reference)
; __global__ void __launch_bounds__(NTHR, 2) fwd_megakernel(Args args) {
;     ...
;     xcd_barrier(gbar);
;     {
;         const int vcu = ((G & 7) == 0) ? (bx & 7) * (G >> 3) + (bx >> 3) : bx;
;         for (int a = vcu; a < 3072; a += G) attn_unit(lds, a, Qb, Kb, Vb, Qb, LSE);
.LBB0_159:
	s_or_b64 exec, exec, s[0:1]
	s_and_b32 s0, s74, 7
	s_cmp_lg_u32 s0, 0
	s_mov_b32 s19, s2
	s_waitcnt lgkmcnt(0)
	s_barrier
	s_cselect_b32 s101, 1, 0
	v_readfirstlane_b32 s98, v181
	s_nop 3
	s_cmp_lt_u32 s98, 0x100
	s_cbranch_scc1 .Lprio_done_2
	s_setprio 1
.Lprio_done_2:
	s_cmp_lg_u32 s101, 0
	s_cbranch_scc1 .LBB0_161
	s_and_b32 s0, s2, 7
	s_ashr_i32 s1, s74, 3
	s_mul_i32 s0, s1, s0
	s_ashr_i32 s1, s2, 3
	s_add_i32 s19, s0, s1

; __device__ __forceinline__ void hgrn_pass_c(LAS unsigned char* lds, int unit, bf16_t* HG, const float* LB, const bf16_t* S, const float* hgain, const bf16_t* Og, const float* lse) {
;     const int tid = threadIdx.x, lane = tid & 63, wid = __builtin_amdgcn_readfirstlane(tid >> 6), r = lane & 31, h = lane >> 5;
;     const int b = unit >> 10, hd = (unit >> 7) & 7, c = unit & 127;
;     hgrn_setup<false>(lds, b, hd, c, HG, LB);
;     const int vb = wid >> 1, tb = wid & 1;
;     const bf16_t* Sg = S + (size_t)unit * 16384;
;     f32x16 o;
; #pragma unroll
;     for (int i = 0; i < 16; ++i) o[i] = 0.f;
;     const int trow = 32 * tb + r, vrow = 32 * vb + r;
;     bf16x8 qf[8];
; #pragma unroll
;     for (int ks = 0; ks < 8; ++ks) qf[ks] = *(const LAS bf16x8*)(lds + HL_QT + trow * 256 + (((2 * ks + h) ^ (trow & 15)) << 4));
; #pragma unroll
;     for (int ks = 0; ks < 8; ++ks) { const bf16x8 af = __builtin_bit_cast(bf16x8, *(const u32x4*)(Sg + vrow * 128 + 16 * ks + 8 * h)); o = MFMA32(af, qf[ks], o); }
;     for (int sb = 0; sb <= tb; ++sb) {
;         f32x16 X;
; #pragma unroll
;         for (int i = 0; i < 16; ++i) X[i] = 0.f;
;         const int srow = 32 * sb + r;
; #pragma unroll
;         for (int ks = 0; ks < 8; ++ks) { const bf16x8 af = *(const LAS bf16x8*)(lds + HL_KT + srow * 256 + (((2 * ks + h) ^ (srow & 15)) << 4)); X = MFMA32(af, qf[ks], X); }
;         if (sb == tb) {
; #pragma unroll
;             for (int i = 0; i < 16; ++i) if (crow(i, h) > r) X[i] = 0.f;
;         }
; #pragma unroll
;         for (int ss = 0; ss < 2; ++ss) {
;             const bf16x8 pb = pack8(X, 8 * ss);
;             const int c0 = 4 * sb + 2 * ss;
;             const u32x2 lo = *(const LAS u32x2*)(lds + HL_VT + vrow * 128 + ((c0 ^ (vrow & 7)) << 4) + 8 * h);
;             const u32x2 hi = *(const LAS u32x2*)(lds + HL_VT + vrow * 128 + (((c0 + 1) ^ (vrow & 7)) << 4) + 8 * h);
;             u32x4 aw; aw.x = lo.x; aw.y = lo.y; aw.z = hi.x; aw.w = hi.y;
;             o = MFMA32(__builtin_bit_cast(bf16x8, aw), pb, o);
;         }
;     }
;     float ssq = 0.f;
; #pragma unroll
;     for (int i = 0; i < 16; ++i) ssq += o[i] * o[i];
;     ssq += __shfl_xor(ssq, 32);
; __global__ void __launch_bounds__(NTHR, 2) fwd_megakernel(Args args) {
;     ...
;     for (int u = bx; u < 2048; u += G) hgrn_pass_c(lds, u, HG, LB, Sb, hgain, Qb, LSE);
;     xcd_barrier(gbar);
.LBB0_374:
	s_or_b64 exec, exec, s[0:1]
	s_andn2_b64 vcc, exec, s[6:7]
	s_waitcnt lgkmcnt(0)
	s_barrier
	s_cselect_b32 s101, 1, 0
	v_readfirstlane_b32 s98, v181
	s_nop 3
	s_cmp_lt_u32 s98, 0x100
	s_cbranch_scc1 .Lprio_done_4
	s_setprio 1
.Lprio_done_4:
	s_cmp_lg_u32 s101, 0
	s_cbranch_vccnz .LBB0_389
	v_xor_b32_e32 v0, v128, v181
	v_lshlrev_b32_e32 v0, 4, v0
	v_and_b32_e32 v5, 0xf0, v0
	v_add_u32_e32 v0, 0x200, v181
	v_lshrrev_b32_e32 v68, 4, v0
	v_xor_b32_e32 v2, v68, v181
	v_lshlrev_b32_e32 v2, 4, v2
	s_movk_i32 s0, 0x104
	v_and_b32_e32 v8, 0xf0, v2
	v_mad_u32_u24 v2, v180, s0, v150
	v_lshrrev_b32_e32 v0, 6, v0
	s_add_i32 s3, 0, 0x19000
	v_lshl_add_u32 v91, v154, 5, v2
	v_lshl_add_u32 v93, v0, 5, v2
	v_and_b32_e32 v2, 0x7f, v181
	s_movk_i32 s4, 0x110
	v_bitop3_b32 v3, v154, v181, 15 bitop3:0x78
	v_lshl_add_u32 v94, v2, 2, 0
	v_mov_b32_e32 v2, s3
	v_lshlrev_b32_e32 v10, 4, v3
	v_bitop3_b32 v3, v0, v181, 15 bitop3:0x78
	v_mad_u32_u24 v13, v180, s4, v2
	s_add_i32 s4, 0, 0x15000
	s_movk_i32 s6, 0x70
	v_mov_b32_e32 v17, 0x70
	s_movk_i32 s10, 0x50
	s_movk_i32 s11, 0x60
	s_movk_i32 s5, 0x200
	v_lshlrev_b32_e32 v11, 4, v3
	v_lshl_add_u32 v2, v154, 10, s4
	v_and_b32_e32 v3, 0x70, v153
	v_bitop3_b32 v18, v153, 16, v17 bitop3:0x6c
	s_movk_i32 s7, 0x80
	v_bitop3_b32 v20, v153, 32, v17 bitop3:0x6c
	s_movk_i32 s8, 0x100
	v_bitop3_b32 v22, v153, 48, v17 bitop3:0x6c
	s_movk_i32 s9, 0x180
	v_bitop3_b32 v24, v153, 64, v17 bitop3:0x6c
	v_bitop3_b32 v26, v153, s10, v17 bitop3:0x6c
	s_movk_i32 s10, 0x280
	v_bitop3_b32 v17, v153, s11, v17 bitop3:0x6c
	s_movk_i32 s11, 0x300
	v_bitop3_b32 v29, v153, s6, v153 bitop3:0xc
	s_movk_i32 s6, 0x380
	v_lshlrev_b32_e32 v92, 3, v0
	v_add_u32_e32 v16, v2, v3
	v_add3_u32 v19, v2, v18, s7
	v_add3_u32 v21, v2, v20, s8
	v_add3_u32 v23, v2, v22, s9
	v_add3_u32 v25, v2, v24, s5
	v_add3_u32 v27, v2, v26, s10
	v_add3_u32 v28, v2, v17, s11
	v_add3_u32 v30, v2, v29, s6
	v_lshlrev_b32_e32 v31, 4, v0
	v_lshl_add_u32 v0, v0, 10, s4
	v_lshlrev_b32_e32 v2, 2, v151
	v_add_u32_e32 v32, v0, v3
	v_or_b32_e32 v3, 2, v2
	v_add3_u32 v20, v0, v20, s8
	v_add3_u32 v22, v0, v22, s9
	v_cmp_gt_u32_e64 s[8:9], v3, v136
	v_or_b32_e32 v3, 3, v2
	v_add3_u32 v26, v0, v26, s10
	v_add3_u32 v17, v0, v17, s11
	v_cmp_gt_u32_e64 s[10:11], v3, v136
	v_or_b32_e32 v3, 8, v2
	v_add3_u32 v18, v0, v18, s7
	v_add3_u32 v24, v0, v24, s5
	v_add3_u32 v29, v0, v29, s6
	v_bitop3_b32 v0, v152, v149, 1 bitop3:0x6c
	v_cmp_gt_u32_e64 s[12:13], v3, v136
	v_or_b32_e32 v3, 9, v2
	v_lshlrev_b32_e32 v95, 4, v0
	v_bitop3_b32 v0, v151, v149, 2 bitop3:0x36
	v_cmp_gt_u32_e64 s[14:15], v3, v136
	v_or_b32_e32 v3, 10, v2
	v_lshlrev_b32_e32 v96, 4, v0
	v_bitop3_b32 v0, v151, v149, 4 bitop3:0x36
	v_cmp_gt_u32_e64 s[16:17], v3, v136
	v_or_b32_e32 v3, 11, v2
	v_lshlrev_b32_e32 v97, 4, v0
	v_bitop3_b32 v0, v151, v149, 6 bitop3:0x36
	v_cmp_gt_u32_e64 s[18:19], v3, v136
	v_or_b32_e32 v3, 16, v2
	v_lshlrev_b32_e32 v98, 4, v0
	v_bitop3_b32 v0, v151, v149, 8 bitop3:0x36
	v_cmp_gt_u32_e64 s[20:21], v3, v136
	v_or_b32_e32 v3, 17, v2
	v_lshlrev_b32_e32 v99, 4, v0
	v_bitop3_b32 v0, v151, v149, 10 bitop3:0x36
	v_cmp_gt_u32_e64 s[22:23], v3, v136
	v_or_b32_e32 v3, 18, v2
	v_lshlrev_b32_e32 v100, 4, v0
	v_bitop3_b32 v0, v151, v149, 12 bitop3:0x36
	v_cmp_gt_u32_e64 s[24:25], v3, v136
	v_or_b32_e32 v3, 19, v2
	v_lshlrev_b32_e32 v101, 4, v0
	v_bitop3_b32 v0, v151, v149, 14 bitop3:0x36
	v_cmp_gt_u32_e64 s[26:27], v3, v136
	v_or_b32_e32 v3, 24, v2
	v_lshlrev_b32_e32 v102, 4, v0
	v_lshlrev_b32_e32 v0, 3, v151
	v_cmp_gt_u32_e64 s[28:29], v3, v136
	v_or_b32_e32 v3, 25, v2
	v_add_u32_e32 v105, s4, v0
	v_cmp_gt_u32_e64 s[4:5], v2, v136
	v_cmp_lt_u32_e64 s[6:7], v2, v136
	v_cmp_gt_u32_e64 s[30:31], v3, v136
	v_or_b32_e32 v3, 26, v2
	v_or_b32_e32 v2, 27, v2
	v_cmp_gt_u32_e64 s[36:37], v2, v136
	v_mbcnt_hi_u32_b32 v2, -1, v200
	v_and_b32_e32 v33, 64, v2
	v_cmp_gt_u32_e64 s[34:35], v3, v136
	v_xor_b32_e32 v3, 32, v2
	v_add_u32_e32 v33, 64, v33
	v_cmp_lt_i32_e32 vcc, v3, v33
	v_lshlrev_b32_e32 v64, 4, v149
	v_mov_b32_e32 v65, 0
	v_cndmask_b32_e32 v2, v2, v3, vcc
	v_add_u32_e32 v1, s3, v64
	v_lshl_add_u32 v4, v128, 8, 0
	v_mul_u32_u24_e32 v6, 0x110, v128
	v_lshl_add_u32 v7, v68, 8, 0
	v_mul_u32_u24_e32 v9, 0x110, v68
	s_movk_i32 s0, 0x7f
	v_mul_u32_u24_e32 v12, 0x2040, v129
	v_and_b32_e32 v14, 14, v153
	v_lshlrev_b32_e32 v15, 4, v154
	v_lshlrev_b32_e32 v106, 4, v148
	v_lshlrev_b32_e32 v110, 2, v2
	v_lshlrev_b32_e32 v2, 5, v149
	v_mov_b32_e32 v3, v65
	v_lshl_add_u64 v[66:67], s[68:69], 0, v[64:65]
	s_mov_b32 s53, 0
	v_mov_b32_e32 v69, v65
	v_lshlrev_b32_e32 v90, 3, v154
	v_cmp_lt_u32_e64 s[0:1], s0, v181
	v_lshlrev_b32_e32 v103, 7, v136
	v_lshl_add_u32 v104, v136, 8, 0
	v_xor_b32_e32 v107, 16, v106
	v_xor_b32_e32 v108, 32, v106
	v_xor_b32_e32 v109, 48, v106
	v_cmp_eq_u32_e64 s[38:39], 0, v151
	v_lshl_add_u64 v[70:71], s[56:57], 0, v[2:3]
	v_lshl_add_u64 v[72:73], s[46:47], 0, v[64:65]
	v_add_u32_e32 v111, s3, v0
	v_add_u32_e32 v112, 0x8100, v94
	s_movk_i32 s43, 0x1000
	v_add_u32_e32 v113, v4, v5
	v_add_u32_e32 v114, v7, v8
	v_add_u32_e32 v115, v13, v15
	v_add_u32_e32 v116, v16, v14
	v_add_u32_e32 v117, v19, v14
	v_add_u32_e32 v118, v21, v14
	v_add_u32_e32 v119, v23, v14
	v_add_u32_e32 v120, v25, v14
	v_add_u32_e32 v121, v27, v14
	v_add_u32_e32 v122, v28, v14
	v_add_u32_e32 v123, v30, v14
	v_add_u32_e32 v124, v13, v31
	v_add_u32_e32 v125, v32, v14
	v_add_u32_e32 v126, v18, v14
	v_add_u32_e32 v127, v20, v14
	v_add_u32_e32 v130, v22, v14
	v_add_u32_e32 v131, v24, v14
	v_add_u32_e32 v132, v26, v14
	v_add_u32_e32 v133, v17, v14
	v_add_u32_e32 v134, v29, v14
	v_lshlrev_b32_e32 v74, 1, v0
	v_mov_b32_e32 v135, 0x358637bd
	s_mov_b32 s66, 0x800000
	s_mov_b32 s67, 0x80000
	s_mov_b32 s86, 0x100000
	s_movk_i32 s87, 0x1800
	v_add_u32_e32 v138, v1, v6
	v_add_u32_e32 v139, v1, v9
	v_add_u32_e32 v140, v150, v10
	v_add_u32_e32 v141, v150, v11
	v_add_u32_e32 v142, v94, v12
	v_mov_b32_e32 v77, 1.0
	s_mov_b32 s56, s2
	s_branch .LBB0_377

; __global__ void __launch_bounds__(NTHR, 2) fwd_megakernel(Args args) {
	.amdhsa_kernel _Z14fwd_megakernel4Args
		.amdhsa_group_segment_fixed_size 0
		.amdhsa_private_segment_fixed_size 0
		.amdhsa_kernarg_size 632
		.amdhsa_user_sgpr_count 2
		.amdhsa_user_sgpr_dispatch_ptr 0
		.amdhsa_user_sgpr_queue_ptr 0
		.amdhsa_user_sgpr_kernarg_segment_ptr 1
		.amdhsa_user_sgpr_dispatch_id 0
		.amdhsa_user_sgpr_kernarg_preload_length 0
		.amdhsa_user_sgpr_kernarg_preload_offset 0
		.amdhsa_user_sgpr_private_segment_size 0
		.amdhsa_uses_dynamic_stack 0
		.amdhsa_enable_private_segment 0
		.amdhsa_system_sgpr_workgroup_id_x 1
		.amdhsa_system_sgpr_workgroup_id_y 0
		.amdhsa_system_sgpr_workgroup_id_z 0
		.amdhsa_system_sgpr_workgroup_info 0
		.amdhsa_system_vgpr_workitem_id 2
		.amdhsa_next_free_vgpr 241
		.amdhsa_next_free_sgpr 102
		.amdhsa_accum_offset 244
		.amdhsa_reserve_vcc 1
		.amdhsa_float_round_mode_32 0
		.amdhsa_float_round_mode_16_64 0
		.amdhsa_float_denorm_mode_32 3
		.amdhsa_float_denorm_mode_16_64 3
		.amdhsa_dx10_clamp 1
		.amdhsa_ieee_mode 1
		.amdhsa_fp16_overflow 0
		.amdhsa_tg_split 0
		.amdhsa_exception_fp_ieee_invalid_op 0
		.amdhsa_exception_fp_denorm_src 0
		.amdhsa_exception_fp_ieee_div_zero 0
		.amdhsa_exception_fp_ieee_overflow 0
		.amdhsa_exception_fp_ieee_underflow 0
		.amdhsa_exception_fp_ieee_inexact 0
		.amdhsa_exception_int_div_zero 0
	.end_amdhsa_kernel

; __global__ void __launch_bounds__(NTHR, 2) fwd_megakernel(Args args) {
amdhsa.kernels:
  - .agpr_count:     0
    .args:
      - .offset:         0
        .size:           376
        .value_kind:     by_value
      - .offset:         376
        .size:           4
        .value_kind:     hidden_block_count_x
      - .offset:         380
        .size:           4
        .value_kind:     hidden_block_count_y
      - .offset:         384
        .size:           4
        .value_kind:     hidden_block_count_z
      - .offset:         388
        .size:           2
        .value_kind:     hidden_group_size_x
      - .offset:         390
        .size:           2
        .value_kind:     hidden_group_size_y
      - .offset:         392
        .size:           2
        .value_kind:     hidden_group_size_z
      - .offset:         394
        .size:           2
        .value_kind:     hidden_remainder_x
      - .offset:         396
        .size:           2
        .value_kind:     hidden_remainder_y
      - .offset:         398
        .size:           2
        .value_kind:     hidden_remainder_z
      - .offset:         416
        .size:           8
        .value_kind:     hidden_global_offset_x
      - .offset:         424
        .size:           8
        .value_kind:     hidden_global_offset_y
      - .offset:         432
        .size:           8
        .value_kind:     hidden_global_offset_z
      - .offset:         440
        .size:           2
        .value_kind:     hidden_grid_dims
      - .offset:         464
        .size:           8
        .value_kind:     hidden_multigrid_sync_arg
      - .offset:         496
        .size:           4
        .value_kind:     hidden_dynamic_lds_size
    .group_segment_fixed_size: 0
    .kernarg_segment_align: 8
    .kernarg_segment_size: 632
    .language:       OpenCL C
    .language_version:
      - 2
      - 0
    .max_flat_workgroup_size: 512
    .name:           _Z14fwd_megakernel4Args
    .private_segment_fixed_size: 0
    .sgpr_count:     108
    .sgpr_spill_count: 3
    .symbol:         _Z14fwd_megakernel4Args.kd
    .uniform_work_group_size: 1
    .uses_dynamic_stack: false
    .vgpr_count:     241
    .vgpr_spill_count: 0
    .wavefront_size: 64
